# defer the last three PV MFMAs of each attention tile into the barrier-to-barrier restaging window (on top of counted PV waits + chain + peel)
# speedup vs baseline: 1.0083x; 1.0020x over previous
.LBB0_1096:
	ds_read_b128 v[64:67], v194 offset:49152
	ds_read_b128 v[68:71], v195 offset:57344
	ds_read_b128 v[214:217], v196 offset:49152
	ds_read_b128 v[224:227], v197 offset:57344
	v_add_f32_e32 v160, 0, v175
	v_add_f32_e32 v160, v223, v160
	s_waitcnt lgkmcnt(3)
	v_mfma_f32_32x32x16_bf16 v[80:95], v[64:67], v[100:103], 0
	v_add_f32_e32 v160, v161, v160
	v_add_f32_e32 v160, v220, v160
	v_add_f32_e32 v160, v162, v160
	v_add_f32_e32 v160, v174, v160
	v_add_f32_e32 v160, v163, v160
	v_add_f32_e32 v160, v173, v160
	v_add_f32_e32 v160, v164, v160
	s_waitcnt lgkmcnt(2)
	v_mfma_f32_32x32x16_bf16 v[64:79], v[68:71], v[100:103], 0
	v_add_f32_e32 v160, v172, v160
	v_add_f32_e32 v160, v165, v160
	v_add_f32_e32 v160, v171, v160
	v_exp_f32_e32 v156, v156
	v_add_f32_e32 v160, v166, v160
	v_exp_f32_e32 v157, v157
	v_add_f32_e32 v160, v170, v160
	s_waitcnt lgkmcnt(1)
	v_mfma_f32_32x32x16_bf16 v[80:95], v[214:217], v[108:111], v[80:95]
	v_exp_f32_e32 v154, v154
	v_add_f32_e32 v160, v167, v160
	v_exp_f32_e32 v155, v155
	v_add_f32_e32 v160, v169, v160
	v_exp_f32_e32 v148, v148
	v_add_f32_e32 v160, v156, v160
	v_exp_f32_e32 v149, v149
	s_waitcnt lgkmcnt(0)
	v_mfma_f32_32x32x16_bf16 v[64:79], v[224:227], v[108:111], v[64:79]
	ds_read_b128 v[214:217], v198 offset:49152
	ds_read_b128 v[224:227], v200 offset:57344
	v_add_f32_e32 v160, v157, v160
	v_exp_f32_e32 v146, v146
	v_add_f32_e32 v160, v154, v160
	v_exp_f32_e32 v147, v147
	v_add_f32_e32 v160, v155, v160
	v_exp_f32_e32 v144, v144
	s_waitcnt lgkmcnt(1)
	v_mfma_f32_32x32x16_bf16 v[80:95], v[214:217], v[96:99], v[80:95]
	v_add_f32_e32 v160, v148, v160
	v_exp_f32_e32 v145, v145
	v_add_f32_e32 v160, v149, v160
	v_exp_f32_e32 v158, v158
	v_add_f32_e32 v160, v146, v160
	v_exp_f32_e32 v159, v159
	v_add_f32_e32 v160, v147, v160
	s_waitcnt lgkmcnt(0)
	v_mfma_f32_32x32x16_bf16 v[64:79], v[224:227], v[96:99], v[64:79]
	ds_read_b128 v[214:217], v199 offset:49152
	ds_read_b128 v[224:227], v201 offset:57344
	v_exp_f32_e32 v152, v152
	v_add_f32_e32 v160, v144, v160
	v_exp_f32_e32 v153, v153
	v_add_f32_e32 v160, v145, v160
	v_exp_f32_e32 v150, v150
	v_add_f32_e32 v160, v158, v160
	s_waitcnt lgkmcnt(1)
	v_mfma_f32_32x32x16_bf16 v[80:95], v[214:217], v[104:107], v[80:95]
	v_exp_f32_e32 v151, v151
	v_add_f32_e32 v160, v159, v160
	v_add_f32_e32 v160, v152, v160
	v_add_f32_e32 v160, v153, v160
	v_add_f32_e32 v160, v150, v160
	v_add_f32_e32 v211, v151, v160
	v_mov_b32_e32 v218, v211
	s_waitcnt lgkmcnt(0)
	v_mfma_f32_32x32x16_bf16 v[64:79], v[224:227], v[104:107], v[64:79]
	ds_read_b128 v[214:217], v202 offset:49152
	ds_read_b128 v[224:227], v203 offset:57344
	v_permlane32_swap_b32_e32 v211, v218
	s_waitcnt lgkmcnt(1)
	v_mfma_f32_32x32x16_bf16 v[80:95], v[214:217], v[116:119], v[80:95]
	s_waitcnt lgkmcnt(0)
	v_mfma_f32_32x32x16_bf16 v[64:79], v[224:227], v[116:119], v[64:79]
	ds_read_b128 v[214:217], v204 offset:49152
	ds_read_b128 v[224:227], v205 offset:57344
	s_waitcnt lgkmcnt(1)
	v_mfma_f32_32x32x16_bf16 v[80:95], v[214:217], v[124:127], v[80:95]
	s_waitcnt lgkmcnt(0)
	v_mfma_f32_32x32x16_bf16 v[64:79], v[224:227], v[124:127], v[64:79]
	ds_read_b128 v[214:217], v206 offset:49152
	ds_read_b128 v[224:227], v208 offset:57344
	s_waitcnt lgkmcnt(1)
	v_mfma_f32_32x32x16_bf16 v[80:95], v[214:217], v[112:115], v[80:95]
	s_waitcnt lgkmcnt(0)
	v_mfma_f32_32x32x16_bf16 v[64:79], v[224:227], v[112:115], v[64:79]
	ds_read_b128 v[214:217], v207 offset:49152
	ds_read_b128 v[224:227], v209 offset:57344
	v_cvt_pk_bf16_f32 v160, v175, v223
	v_cvt_pk_bf16_f32 v161, v161, v220
	v_cvt_pk_bf16_f32 v162, v162, v174
	v_cvt_pk_bf16_f32 v163, v163, v173
	v_cvt_pk_bf16_f32 v164, v164, v172
	v_cvt_pk_bf16_f32 v165, v165, v171
	s_waitcnt lgkmcnt(1)
	v_mfma_f32_32x32x16_bf16 v[80:95], v[214:217], v[120:123], v[80:95]
	v_permlane32_swap_b32_e32 v160, v162
	v_cvt_pk_bf16_f32 v166, v166, v170
	v_cvt_pk_bf16_f32 v167, v167, v169
	v_cvt_pk_bf16_f32 v170, v156, v157
	v_cvt_pk_bf16_f32 v171, v154, v155
	v_cvt_pk_bf16_f32 v172, v148, v149
	s_waitcnt lgkmcnt(0)
	v_mfma_f32_32x32x16_bf16 v[64:79], v[224:227], v[120:123], v[64:79]
	v_cvt_pk_bf16_f32 v173, v146, v147
	v_cvt_pk_bf16_f32 v214, v144, v145
	v_cvt_pk_bf16_f32 v215, v158, v159
	v_cvt_pk_bf16_f32 v216, v152, v153
	v_cvt_pk_bf16_f32 v217, v150, v151
	v_permlane32_swap_b32_e32 v161, v163
	v_permlane32_swap_b32_e32 v164, v166
	v_permlane32_swap_b32_e32 v165, v167
	v_permlane32_swap_b32_e32 v170, v172
	v_permlane32_swap_b32_e32 v171, v173
	v_permlane32_swap_b32_e32 v214, v216
	v_permlane32_swap_b32_e32 v215, v217
	v_lshl_add_u64 v[144:145], v[180:181], 0, s[8:9]
	s_mov_b32 s2, 0x322f0000
	v_add_co_u32_e32 v146, vcc, s2, v144
	s_mov_b32 s2, 0x32318000
	s_nop 0
	v_addc_co_u32_e32 v147, vcc, 0, v145, vcc
	v_add_co_u32_e32 v148, vcc, s2, v144
	v_lshl_add_u64 v[152:153], v[178:179], 0, s[8:9]
	s_nop 0
	v_addc_co_u32_e32 v149, vcc, 0, v145, vcc
	s_mov_b32 s2, 0x41018000
	v_add_co_u32_e32 v154, vcc, s2, v152
	s_mov_b32 s2, 0x4101c000
	s_nop 0
	v_addc_co_u32_e32 v155, vcc, 0, v153, vcc
	v_add_co_u32_e32 v156, vcc, s2, v152
	global_load_dwordx4 v[144:147], v[146:147], off offset:2560
	s_nop 0
	global_load_dwordx4 v[148:151], v[148:149], off offset:2560
	v_addc_co_u32_e32 v157, vcc, 0, v153, vcc
	global_load_dwordx4 v[152:155], v[154:155], off
	s_nop 0
	global_load_dwordx4 v[156:159], v[156:157], off
	ds_read_b64_tr_b16 v[220:221], v189 offset:0
	ds_read_b64_tr_b16 v[222:223], v189 offset:0x800
	ds_read_b64_tr_b16 v[224:225], v189 offset:0x1000
	ds_read_b64_tr_b16 v[226:227], v189 offset:0x1800
	ds_read_b64_tr_b16 v[230:231], v189 offset:0x2000
	ds_read_b64_tr_b16 v[232:233], v189 offset:0x2800
	ds_read_b64_tr_b16 v[238:239], v189 offset:0x3000
	ds_read_b64_tr_b16 v[240:241], v189 offset:0x3800
	s_waitcnt lgkmcnt(6)
	s_nop 0
	v_mfma_f32_32x32x16_bf16 v[0:15], v[160:163], v[220:223], v[0:15]
	ds_read_b64_tr_b16 v[220:221], v189 offset:0x200
	ds_read_b64_tr_b16 v[222:223], v189 offset:0xa00
	s_waitcnt lgkmcnt(6)
	v_mfma_f32_32x32x16_bf16 v[0:15], v[164:167], v[224:227], v[0:15]
	ds_read_b64_tr_b16 v[224:225], v189 offset:0x1200
	ds_read_b64_tr_b16 v[226:227], v189 offset:0x1a00
	s_waitcnt lgkmcnt(6)
	v_mfma_f32_32x32x16_bf16 v[0:15], v[170:173], v[230:233], v[0:15]
	ds_read_b64_tr_b16 v[230:231], v189 offset:0x2200
	ds_read_b64_tr_b16 v[232:233], v189 offset:0x2a00
	s_waitcnt lgkmcnt(6)
	v_mfma_f32_32x32x16_bf16 v[0:15], v[214:217], v[238:241], v[0:15]
	ds_read_b64_tr_b16 v[238:239], v189 offset:0x3200
	ds_read_b64_tr_b16 v[240:241], v189 offset:0x3a00
	s_waitcnt lgkmcnt(6)
	v_mfma_f32_32x32x16_bf16 v[48:63], v[160:163], v[220:223], v[48:63]
	ds_read_b64_tr_b16 v[220:221], v189 offset:0x400
	ds_read_b64_tr_b16 v[222:223], v189 offset:0xc00
	s_waitcnt lgkmcnt(6)
	v_mfma_f32_32x32x16_bf16 v[48:63], v[164:167], v[224:227], v[48:63]
	ds_read_b64_tr_b16 v[224:225], v189 offset:0x1400
	ds_read_b64_tr_b16 v[226:227], v189 offset:0x1c00
	s_waitcnt lgkmcnt(6)
	v_mfma_f32_32x32x16_bf16 v[48:63], v[170:173], v[230:233], v[48:63]
	ds_read_b64_tr_b16 v[230:231], v189 offset:0x2400
	ds_read_b64_tr_b16 v[232:233], v189 offset:0x2c00
	s_waitcnt lgkmcnt(6)
	v_mfma_f32_32x32x16_bf16 v[48:63], v[214:217], v[238:241], v[48:63]
	ds_read_b64_tr_b16 v[238:239], v189 offset:0x3400
	ds_read_b64_tr_b16 v[240:241], v189 offset:0x3c00
	s_waitcnt lgkmcnt(6)
	v_mfma_f32_32x32x16_bf16 v[32:47], v[160:163], v[220:223], v[32:47]
	ds_read_b64_tr_b16 v[220:221], v189 offset:0x600
	ds_read_b64_tr_b16 v[222:223], v189 offset:0xe00
	s_waitcnt lgkmcnt(6)
	v_mfma_f32_32x32x16_bf16 v[32:47], v[164:167], v[224:227], v[32:47]
	ds_read_b64_tr_b16 v[224:225], v189 offset:0x1600
	ds_read_b64_tr_b16 v[226:227], v189 offset:0x1e00
	s_waitcnt lgkmcnt(6)
	v_mfma_f32_32x32x16_bf16 v[32:47], v[170:173], v[230:233], v[32:47]
	ds_read_b64_tr_b16 v[230:231], v189 offset:0x2600
	ds_read_b64_tr_b16 v[232:233], v189 offset:0x2e00
	s_waitcnt lgkmcnt(6)
	v_mfma_f32_32x32x16_bf16 v[32:47], v[214:217], v[238:241], v[32:47]
	ds_read_b64_tr_b16 v[238:239], v189 offset:0x3600
	ds_read_b64_tr_b16 v[240:241], v189 offset:0x3e00
	s_waitcnt lgkmcnt(6)
	v_mfma_f32_32x32x16_bf16 v[16:31], v[160:163], v[220:223], v[16:31]
	v_max_f32_e32 v160, v81, v81
	v_max_f32_e32 v161, v80, v80
	v_max_f32_e32 v160, v161, v160
	v_max3_f32 v160, v160, v82, v83
	v_max3_f32 v160, v160, v84, v85
	v_max3_f32 v160, v160, v86, v87
	v_max3_f32 v160, v160, v88, v89
	v_max3_f32 v160, v160, v90, v91
	v_max3_f32 v160, v160, v92, v93
	v_max3_f32 v160, v160, v94, v95
	v_max3_f32 v160, v160, v64, v65
	v_max3_f32 v160, v160, v66, v67
	v_max3_f32 v160, v160, v68, v69
	v_max3_f32 v160, v160, v70, v71
	v_max3_f32 v160, v160, v72, v73
	v_max3_f32 v160, v160, v74, v75
	v_max3_f32 v160, v160, v76, v77
	v_max3_f32 v160, v160, v78, v79
	v_mov_b32_e32 v161, v160
	s_nop 1
	v_permlane32_swap_b32_e32 v160, v161
	v_max_f32_e32 v161, v161, v161
	v_max_f32_e32 v160, v160, v160
	v_max_f32_e32 v160, v160, v161
	v_sub_f32_e32 v161, v160, v168
	v_cmp_ge_f32_e32 vcc, s90, v161
	v_max_f32_e32 v161, v168, v168
	v_max_f32_e32 v160, v161, v160
	v_sub_f32_e32 v161, v168, v160
	v_mul_f32_e32 v161, 0x3e0293ee, v161
	v_exp_f32_e32 v161, v161
	s_cmp_eq_u64 vcc, exec
	s_cselect_b64 s[38:39], -1, 0
	s_waitcnt lgkmcnt(0)
	s_barrier
	v_mfma_f32_32x32x16_bf16 v[16:31], v[164:167], v[224:227], v[16:31]
	s_waitcnt vmcnt(4)
	v_cndmask_b32_e64 v219, v161, 1.0, s[38:39]
	v_cmp_gt_f32_e32 vcc, 1.0, v219
	s_waitcnt vmcnt(7)
	ds_write_b128 v190, v[128:131]
	s_waitcnt vmcnt(6)
	ds_write_b128 v191, v[132:135]
	v_mfma_f32_32x32x16_bf16 v[16:31], v[170:173], v[230:233], v[16:31]
	s_waitcnt vmcnt(5)
	ds_write_b128 v192, v[136:139] offset:32768
	s_waitcnt vmcnt(4)
	ds_write_b128 v193, v[140:143] offset:32768
	v_mfma_f32_32x32x16_bf16 v[16:31], v[214:217], v[238:241], v[16:31]
	s_cbranch_vccz .LBB0_1100
	s_and_saveexec_b64 s[2:3], s[36:37]
	ds_write_b32 v186, v219 offset:128
	s_or_b64 exec, exec, s[2:3]
	s_waitcnt lgkmcnt(0)
	v_add_u32_e32 v161, s27, v185
	ds_read_b128 v[162:165], v161 offset:224
	ds_read_b128 v[170:173], v161 offset:192
	ds_read_b128 v[214:217], v161 offset:160
	ds_read_b128 v[220:223], v161 offset:128
	s_waitcnt lgkmcnt(3)
	v_pk_mul_f32 v[12:13], v[12:13], v[162:163]
	s_waitcnt lgkmcnt(2)
	v_pk_mul_f32 v[8:9], v[8:9], v[170:171]
	s_waitcnt lgkmcnt(1)
	v_pk_mul_f32 v[4:5], v[4:5], v[214:215]
	v_pk_mul_f32 v[14:15], v[14:15], v[164:165]
	v_pk_mul_f32 v[10:11], v[10:11], v[172:173]
	v_pk_mul_f32 v[6:7], v[6:7], v[216:217]
	s_waitcnt lgkmcnt(0)
	v_pk_mul_f32 v[2:3], v[2:3], v[222:223]
	v_pk_mul_f32 v[0:1], v[0:1], v[220:221]
	v_pk_mul_f32 v[60:61], v[60:61], v[162:163]
	v_pk_mul_f32 v[56:57], v[56:57], v[170:171]
	v_pk_mul_f32 v[52:53], v[52:53], v[214:215]
	v_pk_mul_f32 v[62:63], v[62:63], v[164:165]
	v_pk_mul_f32 v[58:59], v[58:59], v[172:173]
	v_pk_mul_f32 v[54:55], v[54:55], v[216:217]
	v_pk_mul_f32 v[50:51], v[50:51], v[222:223]
	v_pk_mul_f32 v[48:49], v[48:49], v[220:221]
	v_pk_mul_f32 v[44:45], v[44:45], v[162:163]
	v_pk_mul_f32 v[40:41], v[40:41], v[170:171]
	v_pk_mul_f32 v[36:37], v[36:37], v[214:215]
	v_pk_mul_f32 v[46:47], v[46:47], v[164:165]
	v_pk_mul_f32 v[42:43], v[42:43], v[172:173]
	v_pk_mul_f32 v[38:39], v[38:39], v[216:217]
	v_pk_mul_f32 v[34:35], v[34:35], v[222:223]
	v_pk_mul_f32 v[32:33], v[32:33], v[220:221]
	v_pk_mul_f32 v[28:29], v[28:29], v[162:163]
	v_pk_mul_f32 v[24:25], v[24:25], v[170:171]
	v_pk_mul_f32 v[20:21], v[20:21], v[214:215]
	v_pk_mul_f32 v[30:31], v[30:31], v[164:165]
	v_pk_mul_f32 v[26:27], v[26:27], v[172:173]
	v_pk_mul_f32 v[22:23], v[22:23], v[216:217]
	v_pk_mul_f32 v[18:19], v[18:19], v[222:223]
	v_pk_mul_f32 v[16:17], v[16:17], v[220:221]

.LBB0_1102:
	ds_read_b64_tr_b16 v[214:215], v188 offset:0
	ds_read_b64_tr_b16 v[216:217], v188 offset:0x800
	ds_read_b64_tr_b16 v[224:225], v188 offset:0x1000
	ds_read_b64_tr_b16 v[226:227], v188 offset:0x1800
	ds_read_b64_tr_b16 v[230:231], v188 offset:0x2000
	ds_read_b64_tr_b16 v[232:233], v188 offset:0x2800
	ds_read_b64_tr_b16 v[238:239], v188 offset:0x3000
	ds_read_b64_tr_b16 v[240:241], v188 offset:0x3800
	s_waitcnt lgkmcnt(6)
	s_nop 0
	v_mfma_f32_32x32x16_bf16 v[0:15], v[160:163], v[214:217], v[0:15]
	ds_read_b64_tr_b16 v[214:215], v188 offset:0x200
	ds_read_b64_tr_b16 v[216:217], v188 offset:0xa00
	s_waitcnt lgkmcnt(6)
	v_mfma_f32_32x32x16_bf16 v[0:15], v[164:167], v[224:227], v[0:15]
	ds_read_b64_tr_b16 v[224:225], v188 offset:0x1200
	ds_read_b64_tr_b16 v[226:227], v188 offset:0x1a00
	s_waitcnt lgkmcnt(6)
	v_mfma_f32_32x32x16_bf16 v[0:15], v[168:171], v[230:233], v[0:15]
	ds_read_b64_tr_b16 v[230:231], v188 offset:0x2200
	ds_read_b64_tr_b16 v[232:233], v188 offset:0x2a00
	s_waitcnt lgkmcnt(6)
	v_mfma_f32_32x32x16_bf16 v[0:15], v[172:175], v[238:241], v[0:15]
	ds_read_b64_tr_b16 v[238:239], v188 offset:0x3200
	ds_read_b64_tr_b16 v[240:241], v188 offset:0x3a00
	s_waitcnt lgkmcnt(6)
	v_mfma_f32_32x32x16_bf16 v[48:63], v[160:163], v[214:217], v[48:63]
	ds_read_b64_tr_b16 v[214:215], v188 offset:0x400
	ds_read_b64_tr_b16 v[216:217], v188 offset:0xc00
	s_waitcnt lgkmcnt(6)
	v_mfma_f32_32x32x16_bf16 v[48:63], v[164:167], v[224:227], v[48:63]
	ds_read_b64_tr_b16 v[224:225], v188 offset:0x1400
	ds_read_b64_tr_b16 v[226:227], v188 offset:0x1c00
	s_waitcnt lgkmcnt(6)
	v_mfma_f32_32x32x16_bf16 v[48:63], v[168:171], v[230:233], v[48:63]
	ds_read_b64_tr_b16 v[230:231], v188 offset:0x2400
	ds_read_b64_tr_b16 v[232:233], v188 offset:0x2c00
	s_waitcnt lgkmcnt(6)
	v_mfma_f32_32x32x16_bf16 v[48:63], v[172:175], v[238:241], v[48:63]
	ds_read_b64_tr_b16 v[238:239], v188 offset:0x3400
	ds_read_b64_tr_b16 v[240:241], v188 offset:0x3c00
	s_waitcnt lgkmcnt(6)
	v_mfma_f32_32x32x16_bf16 v[32:47], v[160:163], v[214:217], v[32:47]
	ds_read_b64_tr_b16 v[214:215], v188 offset:0x600
	ds_read_b64_tr_b16 v[216:217], v188 offset:0xe00
	s_waitcnt lgkmcnt(6)
	v_mfma_f32_32x32x16_bf16 v[32:47], v[164:167], v[224:227], v[32:47]
	ds_read_b64_tr_b16 v[224:225], v188 offset:0x1600
	ds_read_b64_tr_b16 v[226:227], v188 offset:0x1e00
	s_waitcnt lgkmcnt(6)
	v_mfma_f32_32x32x16_bf16 v[32:47], v[168:171], v[230:233], v[32:47]
	ds_read_b64_tr_b16 v[230:231], v188 offset:0x2600
	ds_read_b64_tr_b16 v[232:233], v188 offset:0x2e00
	s_waitcnt lgkmcnt(6)
	v_mfma_f32_32x32x16_bf16 v[32:47], v[172:175], v[238:241], v[32:47]
	ds_read_b64_tr_b16 v[238:239], v188 offset:0x3600
	ds_read_b64_tr_b16 v[240:241], v188 offset:0x3e00
	s_waitcnt lgkmcnt(6)
	v_mfma_f32_32x32x16_bf16 v[16:31], v[160:163], v[214:217], v[16:31]
	v_max_f32_e32 v160, v81, v81
	v_max_f32_e32 v161, v80, v80
	v_max_f32_e32 v160, v161, v160
	v_max3_f32 v160, v160, v82, v83
	v_max3_f32 v160, v160, v84, v85
	v_max3_f32 v160, v160, v86, v87
	v_max3_f32 v160, v160, v88, v89
	v_max3_f32 v160, v160, v90, v91
	v_max3_f32 v160, v160, v92, v93
	v_max3_f32 v160, v160, v94, v95
	v_max3_f32 v160, v160, v64, v65
	v_max3_f32 v160, v160, v66, v67
	v_max3_f32 v160, v160, v68, v69
	v_max3_f32 v160, v160, v70, v71
	v_max3_f32 v160, v160, v72, v73
	v_max3_f32 v160, v160, v74, v75
	v_max3_f32 v160, v160, v76, v77
	v_max3_f32 v160, v160, v78, v79
	v_mov_b32_e32 v161, v160
	s_nop 1
	v_permlane32_swap_b32_e32 v160, v161
	v_max_f32_e32 v161, v161, v161
	v_max_f32_e32 v160, v160, v160
	v_max_f32_e32 v160, v160, v161
	v_sub_f32_e32 v161, v160, v220
	v_cmp_ge_f32_e32 vcc, s90, v161
	v_max_f32_e32 v161, v220, v220
	v_max_f32_e32 v161, v161, v160
	v_sub_f32_e32 v160, v220, v161
	v_mul_f32_e32 v160, 0x3e0293ee, v160
	v_exp_f32_e32 v160, v160
	s_cmp_eq_u64 vcc, exec
	s_cselect_b64 s[38:39], -1, 0
	s_waitcnt lgkmcnt(0)
	s_barrier
	v_mfma_f32_32x32x16_bf16 v[16:31], v[164:167], v[224:227], v[16:31]
	s_waitcnt vmcnt(4)
	v_cndmask_b32_e64 v160, v160, 1.0, s[38:39]
	v_cmp_gt_f32_e32 vcc, 1.0, v160
	s_waitcnt vmcnt(3)
	ds_write_b128 v190, v[144:147] offset:16384
	s_waitcnt vmcnt(2)
	ds_write_b128 v191, v[148:151] offset:16384
	v_mfma_f32_32x32x16_bf16 v[16:31], v[168:171], v[230:233], v[16:31]
	s_waitcnt vmcnt(1)
	ds_write_b128 v192, v[152:155] offset:49152
	s_waitcnt vmcnt(0)
	ds_write_b128 v193, v[156:159] offset:49152
	v_mfma_f32_32x32x16_bf16 v[16:31], v[172:175], v[238:241], v[16:31]
	s_cbranch_vccz .LBB0_1106
	s_and_saveexec_b64 s[2:3], s[36:37]
	ds_write_b32 v186, v160 offset:128
	s_or_b64 exec, exec, s[2:3]
	s_waitcnt lgkmcnt(0)
	v_add_u32_e32 v156, s27, v185
	ds_read_b128 v[144:147], v156 offset:224
	ds_read_b128 v[148:151], v156 offset:192
	ds_read_b128 v[152:155], v156 offset:160
	ds_read_b128 v[156:159], v156 offset:128
	s_waitcnt lgkmcnt(3)
	v_pk_mul_f32 v[12:13], v[12:13], v[144:145]
	s_waitcnt lgkmcnt(2)
	v_pk_mul_f32 v[8:9], v[8:9], v[148:149]
	s_waitcnt lgkmcnt(1)
	v_pk_mul_f32 v[4:5], v[4:5], v[152:153]
	v_pk_mul_f32 v[14:15], v[14:15], v[146:147]
	v_pk_mul_f32 v[10:11], v[10:11], v[150:151]
	v_pk_mul_f32 v[6:7], v[6:7], v[154:155]
	s_waitcnt lgkmcnt(0)
	v_pk_mul_f32 v[2:3], v[2:3], v[158:159]
	v_pk_mul_f32 v[0:1], v[0:1], v[156:157]
	v_pk_mul_f32 v[60:61], v[60:61], v[144:145]
	v_pk_mul_f32 v[56:57], v[56:57], v[148:149]
	v_pk_mul_f32 v[52:53], v[52:53], v[152:153]
	v_pk_mul_f32 v[62:63], v[62:63], v[146:147]
	v_pk_mul_f32 v[58:59], v[58:59], v[150:151]
	v_pk_mul_f32 v[54:55], v[54:55], v[154:155]
	v_pk_mul_f32 v[50:51], v[50:51], v[158:159]
	v_pk_mul_f32 v[48:49], v[48:49], v[156:157]
	v_pk_mul_f32 v[44:45], v[44:45], v[144:145]
	v_pk_mul_f32 v[40:41], v[40:41], v[148:149]
	v_pk_mul_f32 v[36:37], v[36:37], v[152:153]
	v_pk_mul_f32 v[46:47], v[46:47], v[146:147]
	v_pk_mul_f32 v[42:43], v[42:43], v[150:151]
	v_pk_mul_f32 v[38:39], v[38:39], v[154:155]
	v_pk_mul_f32 v[34:35], v[34:35], v[158:159]
	v_pk_mul_f32 v[32:33], v[32:33], v[156:157]
	v_pk_mul_f32 v[28:29], v[28:29], v[144:145]
	v_pk_mul_f32 v[24:25], v[24:25], v[148:149]
	v_pk_mul_f32 v[20:21], v[20:21], v[152:153]
	v_pk_mul_f32 v[30:31], v[30:31], v[146:147]
	v_pk_mul_f32 v[26:27], v[26:27], v[150:151]
	v_pk_mul_f32 v[22:23], v[22:23], v[154:155]
	v_pk_mul_f32 v[18:19], v[18:19], v[158:159]
	v_pk_mul_f32 v[16:17], v[16:17], v[156:157]

.LBB0_1135:
	ds_read_b128 v[64:67], v194 offset:57344
	ds_read_b128 v[68:71], v212 offset:57344
	ds_read_b128 v[214:217], v197 offset:57344
	ds_read_b128 v[230:233], v211 offset:57344
	v_add_f32_e32 v164, 0, v165
	v_add_f32_e32 v164, v224, v164
	s_waitcnt lgkmcnt(3)
	v_mfma_f32_32x32x16_bf16 v[80:95], v[64:67], v[140:143], 0
	v_add_f32_e32 v164, v166, v164
	v_add_f32_e32 v164, v225, v164
	v_add_f32_e32 v164, v223, v164
	v_add_f32_e32 v164, v226, v164
	v_add_f32_e32 v164, v167, v164
	v_add_f32_e32 v164, v222, v164
	v_add_f32_e32 v164, v172, v164
	s_waitcnt lgkmcnt(2)
	v_mfma_f32_32x32x16_bf16 v[64:79], v[68:71], v[140:143], 0
	v_add_f32_e32 v164, v174, v164
	v_add_f32_e32 v164, v173, v164
	v_add_f32_e32 v164, v175, v164
	v_exp_f32_e32 v158, v158
	v_add_f32_e32 v164, v160, v164
	v_exp_f32_e32 v159, v159
	v_add_f32_e32 v164, v162, v164
	s_waitcnt lgkmcnt(1)
	v_mfma_f32_32x32x16_bf16 v[80:95], v[214:217], v[136:139], v[80:95]
	v_exp_f32_e32 v156, v156
	v_add_f32_e32 v164, v161, v164
	v_exp_f32_e32 v157, v157
	v_add_f32_e32 v164, v163, v164
	v_exp_f32_e32 v152, v152
	v_add_f32_e32 v164, v158, v164
	v_exp_f32_e32 v153, v153
	s_waitcnt lgkmcnt(0)
	v_mfma_f32_32x32x16_bf16 v[64:79], v[230:233], v[136:139], v[64:79]
	ds_read_b128 v[214:217], v196 offset:57344
	ds_read_b128 v[230:233], v210 offset:57344
	v_add_f32_e32 v164, v159, v164
	v_exp_f32_e32 v148, v148
	v_add_f32_e32 v164, v156, v164
	v_exp_f32_e32 v149, v149
	v_add_f32_e32 v164, v157, v164
	v_exp_f32_e32 v146, v146
	s_waitcnt lgkmcnt(1)
	v_mfma_f32_32x32x16_bf16 v[80:95], v[214:217], v[132:135], v[80:95]
	v_add_f32_e32 v164, v152, v164
	v_exp_f32_e32 v147, v147
	v_add_f32_e32 v164, v153, v164
	v_exp_f32_e32 v154, v154
	v_add_f32_e32 v164, v148, v164
	v_exp_f32_e32 v155, v155
	v_add_f32_e32 v164, v149, v164
	s_waitcnt lgkmcnt(0)
	v_mfma_f32_32x32x16_bf16 v[64:79], v[230:233], v[132:135], v[64:79]
	ds_read_b128 v[214:217], v195 offset:57344
	ds_read_b128 v[230:233], v209 offset:57344
	v_exp_f32_e32 v150, v150
	v_add_f32_e32 v164, v146, v164
	v_exp_f32_e32 v151, v151
	v_add_f32_e32 v164, v147, v164
	v_exp_f32_e32 v144, v144
	v_add_f32_e32 v164, v154, v164
	s_waitcnt lgkmcnt(1)
	v_mfma_f32_32x32x16_bf16 v[80:95], v[214:217], v[128:131], v[80:95]
	v_exp_f32_e32 v145, v145
	v_add_f32_e32 v164, v155, v164
	v_add_f32_e32 v164, v150, v164
	v_add_f32_e32 v164, v151, v164
	v_add_f32_e32 v164, v144, v164
	v_add_f32_e32 v219, v145, v164
	v_mov_b32_e32 v220, v219
	s_waitcnt lgkmcnt(0)
	v_mfma_f32_32x32x16_bf16 v[64:79], v[230:233], v[128:131], v[64:79]
	ds_read_b128 v[214:217], v193 offset:57344
	ds_read_b128 v[230:233], v208 offset:57344
	v_permlane32_swap_b32_e32 v219, v220
	s_waitcnt lgkmcnt(1)
	v_mfma_f32_32x32x16_bf16 v[80:95], v[214:217], v[124:127], v[80:95]
	s_waitcnt lgkmcnt(0)
	v_mfma_f32_32x32x16_bf16 v[64:79], v[230:233], v[124:127], v[64:79]
	ds_read_b128 v[214:217], v192 offset:57344
	ds_read_b128 v[230:233], v206 offset:57344
	s_waitcnt lgkmcnt(1)
	v_mfma_f32_32x32x16_bf16 v[80:95], v[214:217], v[120:123], v[80:95]
	s_waitcnt lgkmcnt(0)
	v_mfma_f32_32x32x16_bf16 v[64:79], v[230:233], v[120:123], v[64:79]
	ds_read_b128 v[214:217], v186 offset:57344
	ds_read_b128 v[230:233], v205 offset:57344
	s_waitcnt lgkmcnt(1)
	v_mfma_f32_32x32x16_bf16 v[80:95], v[214:217], v[116:119], v[80:95]
	s_waitcnt lgkmcnt(0)
	v_mfma_f32_32x32x16_bf16 v[64:79], v[230:233], v[116:119], v[64:79]
	ds_read_b128 v[214:217], v189 offset:57344
	ds_read_b128 v[230:233], v204 offset:57344
	s_waitcnt lgkmcnt(1)
	v_mfma_f32_32x32x16_bf16 v[80:95], v[214:217], v[112:115], v[80:95]
	s_waitcnt lgkmcnt(0)
	v_mfma_f32_32x32x16_bf16 v[64:79], v[230:233], v[112:115], v[64:79]
	ds_read_b128 v[214:217], v190 offset:57344
	ds_read_b128 v[230:233], v203 offset:57344
	s_waitcnt lgkmcnt(1)
	v_mfma_f32_32x32x16_bf16 v[80:95], v[214:217], v[108:111], v[80:95]
	s_waitcnt lgkmcnt(0)
	v_mfma_f32_32x32x16_bf16 v[64:79], v[230:233], v[108:111], v[64:79]
	ds_read_b128 v[214:217], v188 offset:57344
	ds_read_b128 v[230:233], v202 offset:57344
	s_waitcnt lgkmcnt(1)
	v_mfma_f32_32x32x16_bf16 v[80:95], v[214:217], v[104:107], v[80:95]
	s_waitcnt lgkmcnt(0)
	v_mfma_f32_32x32x16_bf16 v[64:79], v[230:233], v[104:107], v[64:79]
	ds_read_b128 v[214:217], v199 offset:57344
	ds_read_b128 v[230:233], v201 offset:57344
	s_waitcnt lgkmcnt(1)
	v_mfma_f32_32x32x16_bf16 v[80:95], v[214:217], v[100:103], v[80:95]
	s_waitcnt lgkmcnt(0)
	v_mfma_f32_32x32x16_bf16 v[64:79], v[230:233], v[100:103], v[64:79]
	ds_read_b128 v[214:217], v198 offset:57344
	ds_read_b128 v[230:233], v200 offset:57344
	v_cvt_pk_bf16_f32 v164, v165, v224
	v_cvt_pk_bf16_f32 v165, v166, v225
	v_cvt_pk_bf16_f32 v166, v223, v226
	v_cvt_pk_bf16_f32 v167, v167, v222
	s_nop 0
	v_permlane32_swap_b32_e32 v164, v166
	s_waitcnt lgkmcnt(1)
	v_mfma_f32_32x32x16_bf16 v[80:95], v[214:217], v[96:99], v[80:95]
	v_cvt_pk_bf16_f32 v214, v172, v174
	v_cvt_pk_bf16_f32 v215, v173, v175
	v_cvt_pk_bf16_f32 v216, v160, v162
	v_cvt_pk_bf16_f32 v217, v161, v163
	v_cvt_pk_bf16_f32 v222, v158, v159
	v_cvt_pk_bf16_f32 v223, v156, v157
	v_cvt_pk_bf16_f32 v224, v152, v153
	s_waitcnt lgkmcnt(0)
	v_mfma_f32_32x32x16_bf16 v[64:79], v[230:233], v[96:99], v[64:79]
	v_cvt_pk_bf16_f32 v225, v148, v149
	v_cvt_pk_bf16_f32 v230, v146, v147
	v_cvt_pk_bf16_f32 v231, v154, v155
	v_cvt_pk_bf16_f32 v232, v150, v151
	v_cvt_pk_bf16_f32 v233, v144, v145
	v_permlane32_swap_b32_e32 v165, v167
	v_permlane32_swap_b32_e32 v214, v216
	v_permlane32_swap_b32_e32 v215, v217
	v_permlane32_swap_b32_e32 v222, v224
	v_permlane32_swap_b32_e32 v223, v225
	v_permlane32_swap_b32_e32 v230, v232
	v_permlane32_swap_b32_e32 v231, v233
	v_lshl_add_u64 v[172:173], s[44:45], 0, v[170:171]
	s_mov_b32 s2, 0x4bf80000
	v_add_co_u32_e32 v148, vcc, s2, v172
	s_mov_b32 s2, 0x4bfa0000
	s_nop 0
	v_addc_co_u32_e32 v149, vcc, 0, v173, vcc
	v_add_co_u32_e32 v152, vcc, s2, v172
	v_lshl_add_u64 v[174:175], s[44:45], 0, v[168:169]
	s_nop 0
	v_addc_co_u32_e32 v153, vcc, 0, v173, vcc
	global_load_dwordx4 v[144:147], v[148:149], off offset:256
	s_nop 0
	global_load_dwordx4 v[148:151], v[148:149], off
	s_nop 0
	global_load_dwordx4 v[156:159], v[152:153], off offset:256
	s_nop 0
	global_load_dwordx4 v[152:155], v[152:153], off
	s_mov_b32 s2, 0x45404000
	v_add_co_u32_e32 v160, vcc, s2, v174
	s_nop 1
	v_addc_co_u32_e32 v161, vcc, 0, v175, vcc
	global_load_dwordx4 v[160:163], v[160:161], off
	ds_read_b64_tr_b16 v[238:239], v182 offset:0
	ds_read_b64_tr_b16 v[240:241], v182 offset:0x800
	ds_read_b64_tr_b16 v[242:243], v182 offset:0x1000
	ds_read_b64_tr_b16 v[244:245], v182 offset:0x1800
	ds_read_b64_tr_b16 v[246:247], v182 offset:0x2000
	ds_read_b64_tr_b16 v[248:249], v182 offset:0x2800
	ds_read_b64_tr_b16 v[250:251], v182 offset:0x3000
	ds_read_b64_tr_b16 v[252:253], v182 offset:0x3800
	s_waitcnt lgkmcnt(6)
	s_nop 0
	v_mfma_f32_32x32x16_bf16 v[0:15], v[164:167], v[238:241], v[0:15]
	ds_read_b64_tr_b16 v[238:239], v182 offset:0x200
	ds_read_b64_tr_b16 v[240:241], v182 offset:0xa00
	s_waitcnt lgkmcnt(6)
	v_mfma_f32_32x32x16_bf16 v[0:15], v[214:217], v[242:245], v[0:15]
	ds_read_b64_tr_b16 v[242:243], v182 offset:0x1200
	ds_read_b64_tr_b16 v[244:245], v182 offset:0x1a00
	s_waitcnt lgkmcnt(6)
	v_mfma_f32_32x32x16_bf16 v[0:15], v[222:225], v[246:249], v[0:15]
	ds_read_b64_tr_b16 v[246:247], v182 offset:0x2200
	ds_read_b64_tr_b16 v[248:249], v182 offset:0x2a00
	s_waitcnt lgkmcnt(6)
	v_mfma_f32_32x32x16_bf16 v[0:15], v[230:233], v[250:253], v[0:15]
	ds_read_b64_tr_b16 v[250:251], v182 offset:0x3200
	ds_read_b64_tr_b16 v[252:253], v182 offset:0x3a00
	s_waitcnt lgkmcnt(6)
	v_mfma_f32_32x32x16_bf16 v[48:63], v[164:167], v[238:241], v[48:63]
	ds_read_b64_tr_b16 v[238:239], v182 offset:0x400
	ds_read_b64_tr_b16 v[240:241], v182 offset:0xc00
	s_waitcnt lgkmcnt(6)
	v_mfma_f32_32x32x16_bf16 v[48:63], v[214:217], v[242:245], v[48:63]
	ds_read_b64_tr_b16 v[242:243], v182 offset:0x1400
	ds_read_b64_tr_b16 v[244:245], v182 offset:0x1c00
	s_waitcnt lgkmcnt(6)
	v_mfma_f32_32x32x16_bf16 v[48:63], v[222:225], v[246:249], v[48:63]
	ds_read_b64_tr_b16 v[246:247], v182 offset:0x2400
	ds_read_b64_tr_b16 v[248:249], v182 offset:0x2c00
	s_waitcnt lgkmcnt(6)
	v_mfma_f32_32x32x16_bf16 v[48:63], v[230:233], v[250:253], v[48:63]
	ds_read_b64_tr_b16 v[250:251], v182 offset:0x3400
	ds_read_b64_tr_b16 v[252:253], v182 offset:0x3c00
	s_waitcnt lgkmcnt(6)
	v_mfma_f32_32x32x16_bf16 v[32:47], v[164:167], v[238:241], v[32:47]
	ds_read_b64_tr_b16 v[238:239], v182 offset:0x600
	ds_read_b64_tr_b16 v[240:241], v182 offset:0xe00
	s_waitcnt lgkmcnt(6)
	v_mfma_f32_32x32x16_bf16 v[32:47], v[214:217], v[242:245], v[32:47]
	ds_read_b64_tr_b16 v[242:243], v182 offset:0x1600
	ds_read_b64_tr_b16 v[244:245], v182 offset:0x1e00
	s_waitcnt lgkmcnt(6)
	v_mfma_f32_32x32x16_bf16 v[32:47], v[222:225], v[246:249], v[32:47]
	ds_read_b64_tr_b16 v[246:247], v182 offset:0x2600
	ds_read_b64_tr_b16 v[248:249], v182 offset:0x2e00
	s_waitcnt lgkmcnt(6)
	v_mfma_f32_32x32x16_bf16 v[32:47], v[230:233], v[250:253], v[32:47]
	ds_read_b64_tr_b16 v[250:251], v182 offset:0x3600
	ds_read_b64_tr_b16 v[252:253], v182 offset:0x3e00
	s_waitcnt lgkmcnt(6)
	v_mfma_f32_32x32x16_bf16 v[16:31], v[164:167], v[238:241], v[16:31]
	v_max_f32_e32 v164, v81, v81
	v_max_f32_e32 v165, v80, v80
	v_max_f32_e32 v164, v165, v164
	v_max3_f32 v164, v164, v82, v83
	v_max3_f32 v164, v164, v84, v85
	v_max3_f32 v164, v164, v86, v87
	v_max3_f32 v164, v164, v88, v89
	v_max3_f32 v164, v164, v90, v91
	v_max3_f32 v164, v164, v92, v93
	v_max3_f32 v164, v164, v94, v95
	v_max3_f32 v164, v164, v64, v65
	v_max3_f32 v164, v164, v66, v67
	v_max3_f32 v164, v164, v68, v69
	v_max3_f32 v164, v164, v70, v71
	v_max3_f32 v164, v164, v72, v73
	v_max3_f32 v164, v164, v74, v75
	v_max3_f32 v164, v164, v76, v77
	v_max3_f32 v164, v164, v78, v79
	v_mov_b32_e32 v165, v164
	s_nop 1
	v_permlane32_swap_b32_e32 v164, v165
	v_max_f32_e32 v165, v165, v165
	v_max_f32_e32 v164, v164, v164
	v_max_f32_e32 v164, v164, v165
	v_sub_f32_e32 v165, v164, v207
	v_cmp_ge_f32_e32 vcc, s46, v165
	v_max_f32_e32 v165, v207, v207
	v_max_f32_e32 v164, v165, v164
	v_sub_f32_e32 v165, v207, v164
	v_mul_f32_e32 v165, 0x3dd53b94, v165
	v_exp_f32_e32 v165, v165
	s_cmp_eq_u64 vcc, exec
	s_cselect_b64 s[38:39], -1, 0
	s_waitcnt lgkmcnt(0)
	s_barrier
	v_mfma_f32_32x32x16_bf16 v[16:31], v[214:217], v[242:245], v[16:31]
	s_waitcnt vmcnt(0)
	v_cndmask_b32_e64 v221, v165, 1.0, s[38:39]
	v_cmp_gt_f32_e32 vcc, 1.0, v221
	s_waitcnt vmcnt(4)
	ds_write_b128 v183, v[144:147]
	s_waitcnt vmcnt(2)
	ds_write_b128 v184, v[156:159]
	v_mfma_f32_32x32x16_bf16 v[16:31], v[222:225], v[246:249], v[16:31]
	ds_write_b128 v185, v[148:151] offset:32768
	s_waitcnt vmcnt(1)
	ds_write_b128 v187, v[152:155] offset:32768
	s_waitcnt vmcnt(0)
	ds_write_b128 v191, v[160:163] offset:32768
	v_mfma_f32_32x32x16_bf16 v[16:31], v[230:233], v[250:253], v[16:31]
	s_cbranch_vccz .LBB0_1139
	s_and_saveexec_b64 s[2:3], s[36:37]
	ds_write_b32 v179, v221 offset:128
	s_or_b64 exec, exec, s[2:3]
	s_waitcnt lgkmcnt(0)
	v_add_u32_e32 v156, s14, v178
	ds_read_b128 v[144:147], v156 offset:224
	ds_read_b128 v[148:151], v156 offset:192
	ds_read_b128 v[152:155], v156 offset:160
	ds_read_b128 v[156:159], v156 offset:128
	s_waitcnt lgkmcnt(3)
	v_pk_mul_f32 v[12:13], v[12:13], v[144:145]
	s_waitcnt lgkmcnt(2)
	v_pk_mul_f32 v[8:9], v[8:9], v[148:149]
	s_waitcnt lgkmcnt(1)
	v_pk_mul_f32 v[4:5], v[4:5], v[152:153]
	v_pk_mul_f32 v[14:15], v[14:15], v[146:147]
	v_pk_mul_f32 v[10:11], v[10:11], v[150:151]
	v_pk_mul_f32 v[6:7], v[6:7], v[154:155]
	s_waitcnt lgkmcnt(0)
	v_pk_mul_f32 v[2:3], v[2:3], v[158:159]
	v_pk_mul_f32 v[0:1], v[0:1], v[156:157]
	v_pk_mul_f32 v[60:61], v[60:61], v[144:145]
	v_pk_mul_f32 v[56:57], v[56:57], v[148:149]
	v_pk_mul_f32 v[52:53], v[52:53], v[152:153]
	v_pk_mul_f32 v[62:63], v[62:63], v[146:147]
	v_pk_mul_f32 v[58:59], v[58:59], v[150:151]
	v_pk_mul_f32 v[54:55], v[54:55], v[154:155]
	v_pk_mul_f32 v[50:51], v[50:51], v[158:159]
	v_pk_mul_f32 v[48:49], v[48:49], v[156:157]
	v_pk_mul_f32 v[44:45], v[44:45], v[144:145]
	v_pk_mul_f32 v[40:41], v[40:41], v[148:149]
	v_pk_mul_f32 v[36:37], v[36:37], v[152:153]
	v_pk_mul_f32 v[46:47], v[46:47], v[146:147]
	v_pk_mul_f32 v[42:43], v[42:43], v[150:151]
	v_pk_mul_f32 v[38:39], v[38:39], v[154:155]
	v_pk_mul_f32 v[34:35], v[34:35], v[158:159]
	v_pk_mul_f32 v[32:33], v[32:33], v[156:157]
	v_pk_mul_f32 v[28:29], v[28:29], v[144:145]
	v_pk_mul_f32 v[24:25], v[24:25], v[148:149]
	v_pk_mul_f32 v[20:21], v[20:21], v[152:153]
	v_pk_mul_f32 v[30:31], v[30:31], v[146:147]
	v_pk_mul_f32 v[26:27], v[26:27], v[150:151]
	v_pk_mul_f32 v[22:23], v[22:23], v[154:155]
	v_pk_mul_f32 v[18:19], v[18:19], v[158:159]
	v_pk_mul_f32 v[16:17], v[16:17], v[156:157]
.LBB0_1139:
	v_cndmask_b32_e64 v207, v164, v207, s[38:39]
	v_mul_f32_e32 v160, 0xbdd53b94, v207
	v_fmamk_f32 v80, v80, 0x3dd53b94, v160
	v_fmamk_f32 v81, v81, 0x3dd53b94, v160
	v_fmamk_f32 v82, v82, 0x3dd53b94, v160
	v_fmamk_f32 v83, v83, 0x3dd53b94, v160
	v_fmamk_f32 v84, v84, 0x3dd53b94, v160
	v_fmamk_f32 v85, v85, 0x3dd53b94, v160
	v_fmamk_f32 v86, v86, 0x3dd53b94, v160
	v_fmamk_f32 v87, v87, 0x3dd53b94, v160
	v_fmamk_f32 v88, v88, 0x3dd53b94, v160
	v_fmamk_f32 v89, v89, 0x3dd53b94, v160
	v_fmamk_f32 v90, v90, 0x3dd53b94, v160
	v_fmamk_f32 v91, v91, 0x3dd53b94, v160
	v_fmamk_f32 v92, v92, 0x3dd53b94, v160
	v_fmamk_f32 v93, v93, 0x3dd53b94, v160
	v_fmamk_f32 v94, v94, 0x3dd53b94, v160
	v_fmamk_f32 v95, v95, 0x3dd53b94, v160
	v_fmamk_f32 v227, v68, 0x3dd53b94, v160
	v_fmamk_f32 v164, v71, 0x3dd53b94, v160
	v_fmamk_f32 v165, v72, 0x3dd53b94, v160
	v_fmamk_f32 v238, v77, 0x3dd53b94, v160
	v_fmamk_f32 v223, v64, 0x3dd53b94, v160
	v_fmamk_f32 v224, v65, 0x3dd53b94, v160
	v_fmamk_f32 v225, v66, 0x3dd53b94, v160
	v_fmamk_f32 v226, v67, 0x3dd53b94, v160
	v_fmamk_f32 v162, v69, 0x3dd53b94, v160
	v_fmamk_f32 v163, v70, 0x3dd53b94, v160
	v_fmamk_f32 v166, v73, 0x3dd53b94, v160
	v_fmamk_f32 v167, v74, 0x3dd53b94, v160
	v_fmamk_f32 v222, v75, 0x3dd53b94, v160
	v_fmamk_f32 v161, v76, 0x3dd53b94, v160
	v_exp_f32_e32 v157, v80
	v_exp_f32_e32 v159, v81
	v_exp_f32_e32 v155, v82
	v_exp_f32_e32 v158, v83
	v_exp_f32_e32 v154, v84
	v_exp_f32_e32 v156, v85
	v_exp_f32_e32 v152, v86
	v_exp_f32_e32 v153, v87
	v_exp_f32_e32 v149, v88
	v_exp_f32_e32 v151, v89
	v_exp_f32_e32 v148, v90
	v_exp_f32_e32 v150, v91
	v_exp_f32_e32 v145, v92
	v_exp_f32_e32 v147, v93
	v_exp_f32_e32 v144, v94
	v_exp_f32_e32 v146, v95
	v_fmamk_f32 v239, v78, 0x3dd53b94, v160
	v_fmac_f32_e32 v160, 0x3dd53b94, v79
	s_waitcnt lgkmcnt(0)
	s_barrier
	ds_read_b128 v[64:67], v194 offset:32768
	ds_read_b128 v[68:71], v194 offset:45056
	ds_read_b128 v[214:217], v197 offset:32768
	ds_read_b128 v[230:233], v197 offset:45056
	v_exp_f32_e32 v223, v223
	v_exp_f32_e32 v224, v224
	s_waitcnt lgkmcnt(3)
	v_mfma_f32_32x32x16_bf16 v[80:95], v[64:67], v[140:143], 0
	v_exp_f32_e32 v225, v225
	v_exp_f32_e32 v226, v226
	v_exp_f32_e32 v162, v162
	v_exp_f32_e32 v163, v163
	v_exp_f32_e32 v234, v167
	v_exp_f32_e32 v235, v222
	v_exp_f32_e32 v161, v161
	s_waitcnt lgkmcnt(2)
	v_mfma_f32_32x32x16_bf16 v[64:79], v[68:71], v[140:143], 0
	v_exp_f32_e32 v240, v238
	v_exp_f32_e32 v239, v239
	v_exp_f32_e32 v160, v160
	s_waitcnt lgkmcnt(0)
	v_mfma_f32_32x32x16_bf16 v[64:79], v[230:233], v[136:139], v[64:79]
	v_mfma_f32_32x32x16_bf16 v[80:95], v[214:217], v[136:139], v[80:95]
	ds_read_b128 v[214:217], v196 offset:32768
	ds_read_b128 v[230:233], v196 offset:45056
	s_waitcnt lgkmcnt(0)
	v_mfma_f32_32x32x16_bf16 v[64:79], v[230:233], v[132:135], v[64:79]
	v_mfma_f32_32x32x16_bf16 v[80:95], v[214:217], v[132:135], v[80:95]
	ds_read_b128 v[214:217], v195 offset:32768
	ds_read_b128 v[230:233], v195 offset:45056
	s_waitcnt lgkmcnt(0)
	v_mfma_f32_32x32x16_bf16 v[64:79], v[230:233], v[128:131], v[64:79]
	v_mfma_f32_32x32x16_bf16 v[80:95], v[214:217], v[128:131], v[80:95]
	ds_read_b128 v[214:217], v193 offset:32768
	ds_read_b128 v[230:233], v193 offset:45056
	s_waitcnt lgkmcnt(0)
	v_mfma_f32_32x32x16_bf16 v[64:79], v[230:233], v[124:127], v[64:79]
	v_mfma_f32_32x32x16_bf16 v[80:95], v[214:217], v[124:127], v[80:95]
	ds_read_b128 v[214:217], v192 offset:32768
	ds_read_b128 v[230:233], v192 offset:45056
	s_waitcnt lgkmcnt(0)
	v_mfma_f32_32x32x16_bf16 v[64:79], v[230:233], v[120:123], v[64:79]
	v_mfma_f32_32x32x16_bf16 v[80:95], v[214:217], v[120:123], v[80:95]
	ds_read_b128 v[214:217], v186 offset:32768
	ds_read_b128 v[230:233], v186 offset:45056
	s_waitcnt lgkmcnt(0)
	v_mfma_f32_32x32x16_bf16 v[64:79], v[230:233], v[116:119], v[64:79]
	v_mfma_f32_32x32x16_bf16 v[80:95], v[214:217], v[116:119], v[80:95]
	ds_read_b128 v[214:217], v189 offset:32768
	ds_read_b128 v[230:233], v189 offset:45056
	s_waitcnt lgkmcnt(0)
	v_mfma_f32_32x32x16_bf16 v[64:79], v[230:233], v[112:115], v[64:79]
	v_mfma_f32_32x32x16_bf16 v[80:95], v[214:217], v[112:115], v[80:95]
	ds_read_b128 v[214:217], v190 offset:32768
	ds_read_b128 v[230:233], v190 offset:45056
	s_waitcnt lgkmcnt(0)
	v_mfma_f32_32x32x16_bf16 v[64:79], v[230:233], v[108:111], v[64:79]
	v_mfma_f32_32x32x16_bf16 v[80:95], v[214:217], v[108:111], v[80:95]
	ds_read_b128 v[214:217], v188 offset:32768
	ds_read_b128 v[230:233], v188 offset:45056
	s_waitcnt lgkmcnt(0)
	v_mfma_f32_32x32x16_bf16 v[64:79], v[230:233], v[104:107], v[64:79]
	v_mfma_f32_32x32x16_bf16 v[80:95], v[214:217], v[104:107], v[80:95]
	ds_read_b128 v[214:217], v199 offset:32768
	ds_read_b128 v[230:233], v199 offset:45056
	s_waitcnt lgkmcnt(0)
	v_mfma_f32_32x32x16_bf16 v[64:79], v[230:233], v[100:103], v[64:79]
	v_mfma_f32_32x32x16_bf16 v[80:95], v[214:217], v[100:103], v[80:95]
	ds_read_b128 v[214:217], v198 offset:32768
	ds_read_b128 v[230:233], v198 offset:45056
	s_waitcnt lgkmcnt(0)
	v_mfma_f32_32x32x16_bf16 v[64:79], v[230:233], v[96:99], v[64:79]
	v_exp_f32_e32 v231, v164
	v_add_f32_e32 v164, 0, v157
	v_add_f32_e32 v164, v159, v164
	v_add_f32_e32 v164, v155, v164
	v_add_f32_e32 v164, v158, v164
	v_add_f32_e32 v164, v154, v164
	v_add_f32_e32 v164, v156, v164
	v_add_f32_e32 v164, v152, v164
	v_add_f32_e32 v164, v153, v164
	v_add_f32_e32 v164, v149, v164
	v_add_f32_e32 v164, v151, v164
	v_add_f32_e32 v164, v148, v164
	v_add_f32_e32 v164, v150, v164
	v_add_f32_e32 v164, v145, v164
	v_add_f32_e32 v164, v147, v164
	v_add_f32_e32 v164, v144, v164
	v_add_f32_e32 v164, v146, v164
	v_exp_f32_e32 v230, v227
	v_add_f32_e32 v164, v223, v164
	v_add_f32_e32 v164, v224, v164
	v_add_f32_e32 v164, v225, v164
	v_add_f32_e32 v164, v226, v164
	v_exp_f32_e32 v232, v165
	v_add_f32_e32 v164, v230, v164
	v_exp_f32_e32 v233, v166
	v_add_f32_e32 v164, v162, v164
	v_add_f32_e32 v164, v163, v164
	v_add_f32_e32 v164, v231, v164
	v_add_f32_e32 v164, v232, v164
	v_add_f32_e32 v164, v233, v164
	v_mfma_f32_32x32x16_bf16 v[80:95], v[214:217], v[96:99], v[80:95]
	v_add_f32_e32 v164, v234, v164
	v_add_f32_e32 v164, v235, v164
	v_add_f32_e32 v164, v161, v164
	v_add_f32_e32 v164, v240, v164
	v_add_f32_e32 v164, v239, v164
	v_add_f32_e32 v227, v160, v164
	v_mov_b32_e32 v238, v227
	v_cvt_pk_bf16_f32 v164, v157, v159
	v_cvt_pk_bf16_f32 v165, v155, v158
	v_cvt_pk_bf16_f32 v166, v154, v156
	v_cvt_pk_bf16_f32 v167, v152, v153
	s_nop 1
	v_permlane32_swap_b32_e32 v227, v238
	v_permlane32_swap_b32_e32 v164, v166
	v_permlane32_swap_b32_e32 v165, v167
	v_cvt_pk_bf16_f32 v214, v149, v151
	v_cvt_pk_bf16_f32 v215, v148, v150
	v_cvt_pk_bf16_f32 v216, v145, v147
	v_cvt_pk_bf16_f32 v217, v144, v146
	v_cvt_pk_bf16_f32 v222, v223, v224
	v_cvt_pk_bf16_f32 v223, v225, v226
	v_cvt_pk_bf16_f32 v224, v230, v162
	v_cvt_pk_bf16_f32 v225, v163, v231
	v_cvt_pk_bf16_f32 v230, v232, v233
	v_cvt_pk_bf16_f32 v231, v234, v235
	v_cvt_pk_bf16_f32 v232, v161, v240
	v_cvt_pk_bf16_f32 v233, v239, v160
	s_nop 0
	v_permlane32_swap_b32_e32 v214, v216
	v_permlane32_swap_b32_e32 v215, v217
	v_permlane32_swap_b32_e32 v222, v224
	v_permlane32_swap_b32_e32 v223, v225
	v_permlane32_swap_b32_e32 v230, v232
	v_permlane32_swap_b32_e32 v231, v233
	s_mov_b32 s2, 0x4bfc0000
	v_add_co_u32_e32 v148, vcc, s2, v172
	s_mov_b32 s2, 0x4bfe0000
	s_nop 0
	v_addc_co_u32_e32 v149, vcc, 0, v173, vcc
	v_add_co_u32_e32 v152, vcc, s2, v172
	s_mov_b32 s2, 0x45406000
	s_nop 0
	v_addc_co_u32_e32 v153, vcc, 0, v173, vcc
	global_load_dwordx4 v[144:147], v[148:149], off offset:256
	s_nop 0
	global_load_dwordx4 v[148:151], v[148:149], off
	s_nop 0
	global_load_dwordx4 v[156:159], v[152:153], off offset:256
	s_nop 0
	global_load_dwordx4 v[152:155], v[152:153], off
	v_add_co_u32_e32 v160, vcc, s2, v174
	s_nop 1
	v_addc_co_u32_e32 v161, vcc, 0, v175, vcc
	global_load_dwordx4 v[160:163], v[160:161], off
	ds_read_b64_tr_b16 v[172:173], v181 offset:0
	ds_read_b64_tr_b16 v[174:175], v181 offset:0x800
	ds_read_b64_tr_b16 v[240:241], v181 offset:0x1000
	ds_read_b64_tr_b16 v[242:243], v181 offset:0x1800
	ds_read_b64_tr_b16 v[244:245], v181 offset:0x2000
	ds_read_b64_tr_b16 v[246:247], v181 offset:0x2800
	ds_read_b64_tr_b16 v[248:249], v181 offset:0x3000
	ds_read_b64_tr_b16 v[250:251], v181 offset:0x3800
	s_waitcnt lgkmcnt(6)
	s_nop 0
	v_mfma_f32_32x32x16_bf16 v[0:15], v[164:167], v[172:175], v[0:15]
	ds_read_b64_tr_b16 v[172:173], v181 offset:0x200
	ds_read_b64_tr_b16 v[174:175], v181 offset:0xa00
	s_waitcnt lgkmcnt(6)
	v_mfma_f32_32x32x16_bf16 v[0:15], v[214:217], v[240:243], v[0:15]
	ds_read_b64_tr_b16 v[240:241], v181 offset:0x1200
	ds_read_b64_tr_b16 v[242:243], v181 offset:0x1a00
	s_waitcnt lgkmcnt(6)
	v_mfma_f32_32x32x16_bf16 v[0:15], v[222:225], v[244:247], v[0:15]
	ds_read_b64_tr_b16 v[244:245], v181 offset:0x2200
	ds_read_b64_tr_b16 v[246:247], v181 offset:0x2a00
	s_waitcnt lgkmcnt(6)
	v_mfma_f32_32x32x16_bf16 v[0:15], v[230:233], v[248:251], v[0:15]
	ds_read_b64_tr_b16 v[248:249], v181 offset:0x3200
	ds_read_b64_tr_b16 v[250:251], v181 offset:0x3a00
	s_waitcnt lgkmcnt(6)
	v_mfma_f32_32x32x16_bf16 v[48:63], v[164:167], v[172:175], v[48:63]
	ds_read_b64_tr_b16 v[172:173], v181 offset:0x400
	ds_read_b64_tr_b16 v[174:175], v181 offset:0xc00
	s_waitcnt lgkmcnt(6)
	v_mfma_f32_32x32x16_bf16 v[48:63], v[214:217], v[240:243], v[48:63]
	ds_read_b64_tr_b16 v[240:241], v181 offset:0x1400
	ds_read_b64_tr_b16 v[242:243], v181 offset:0x1c00
	s_waitcnt lgkmcnt(6)
	v_mfma_f32_32x32x16_bf16 v[48:63], v[222:225], v[244:247], v[48:63]
	ds_read_b64_tr_b16 v[244:245], v181 offset:0x2400
	ds_read_b64_tr_b16 v[246:247], v181 offset:0x2c00
	s_waitcnt lgkmcnt(6)
	v_mfma_f32_32x32x16_bf16 v[48:63], v[230:233], v[248:251], v[48:63]
	ds_read_b64_tr_b16 v[248:249], v181 offset:0x3400
	ds_read_b64_tr_b16 v[250:251], v181 offset:0x3c00
	s_waitcnt lgkmcnt(6)
	v_mfma_f32_32x32x16_bf16 v[32:47], v[164:167], v[172:175], v[32:47]
	ds_read_b64_tr_b16 v[172:173], v181 offset:0x600
	ds_read_b64_tr_b16 v[174:175], v181 offset:0xe00
	s_waitcnt lgkmcnt(6)
	v_mfma_f32_32x32x16_bf16 v[32:47], v[214:217], v[240:243], v[32:47]
	ds_read_b64_tr_b16 v[240:241], v181 offset:0x1600
	ds_read_b64_tr_b16 v[242:243], v181 offset:0x1e00
	s_waitcnt lgkmcnt(6)
	v_mfma_f32_32x32x16_bf16 v[32:47], v[222:225], v[244:247], v[32:47]
	ds_read_b64_tr_b16 v[244:245], v181 offset:0x2600
	ds_read_b64_tr_b16 v[246:247], v181 offset:0x2e00
	s_waitcnt lgkmcnt(6)
	v_mfma_f32_32x32x16_bf16 v[32:47], v[230:233], v[248:251], v[32:47]
	ds_read_b64_tr_b16 v[248:249], v181 offset:0x3600
	ds_read_b64_tr_b16 v[250:251], v181 offset:0x3e00
	s_waitcnt lgkmcnt(6)
	v_mfma_f32_32x32x16_bf16 v[16:31], v[164:167], v[172:175], v[16:31]
	v_max_f32_e32 v164, v81, v81
	v_max_f32_e32 v165, v80, v80
	v_max_f32_e32 v164, v165, v164
	v_max3_f32 v164, v164, v82, v83
	v_max3_f32 v164, v164, v84, v85
	v_max3_f32 v164, v164, v86, v87
	v_max3_f32 v164, v164, v88, v89
	v_max3_f32 v164, v164, v90, v91
	v_max3_f32 v164, v164, v92, v93
	v_max3_f32 v164, v164, v94, v95
	v_max3_f32 v164, v164, v64, v65
	v_max3_f32 v164, v164, v66, v67
	v_max3_f32 v164, v164, v68, v69
	v_max3_f32 v164, v164, v70, v71
	v_max3_f32 v164, v164, v72, v73
	v_max3_f32 v164, v164, v74, v75
	v_max3_f32 v164, v164, v76, v77
	v_max3_f32 v164, v164, v78, v79
	v_mov_b32_e32 v165, v164
	s_nop 1
	v_permlane32_swap_b32_e32 v164, v165
	v_max_f32_e32 v165, v165, v165
	v_max_f32_e32 v164, v164, v164
	v_max_f32_e32 v164, v164, v165
	v_sub_f32_e32 v165, v164, v207
	v_cmp_ge_f32_e32 vcc, s46, v165
	v_max_f32_e32 v165, v207, v207
	v_max_f32_e32 v165, v165, v164
	v_sub_f32_e32 v164, v207, v165
	v_mul_f32_e32 v164, 0x3dd53b94, v164
	v_exp_f32_e32 v164, v164
	s_cmp_eq_u64 vcc, exec
	s_cselect_b64 s[38:39], -1, 0
	s_waitcnt lgkmcnt(0)
	s_barrier
	v_mfma_f32_32x32x16_bf16 v[16:31], v[214:217], v[240:243], v[16:31]
	s_waitcnt vmcnt(0)
	v_cndmask_b32_e64 v164, v164, 1.0, s[38:39]
	v_cmp_gt_f32_e32 vcc, 1.0, v164
	s_waitcnt vmcnt(4)
	ds_write_b128 v183, v[144:147] offset:16384
	s_waitcnt vmcnt(2)
	ds_write_b128 v184, v[156:159] offset:16384
	v_mfma_f32_32x32x16_bf16 v[16:31], v[222:225], v[244:247], v[16:31]
	ds_write_b128 v185, v[148:151] offset:57344
	s_waitcnt vmcnt(1)
	ds_write_b128 v187, v[152:155] offset:57344
	s_waitcnt vmcnt(0)
	ds_write_b128 v191, v[160:163] offset:57344
	v_mfma_f32_32x32x16_bf16 v[16:31], v[230:233], v[248:251], v[16:31]
	s_cbranch_vccz .LBB0_1143
	s_and_saveexec_b64 s[2:3], s[36:37]
	ds_write_b32 v179, v164 offset:128
	s_or_b64 exec, exec, s[2:3]
	s_waitcnt lgkmcnt(0)
	v_add_u32_e32 v156, s14, v178
	ds_read_b128 v[144:147], v156 offset:224
	ds_read_b128 v[148:151], v156 offset:192
	ds_read_b128 v[152:155], v156 offset:160
	ds_read_b128 v[156:159], v156 offset:128
	s_waitcnt lgkmcnt(3)
	v_pk_mul_f32 v[12:13], v[12:13], v[144:145]
	s_waitcnt lgkmcnt(2)
	v_pk_mul_f32 v[8:9], v[8:9], v[148:149]
	s_waitcnt lgkmcnt(1)
	v_pk_mul_f32 v[4:5], v[4:5], v[152:153]
	v_pk_mul_f32 v[14:15], v[14:15], v[146:147]
	v_pk_mul_f32 v[10:11], v[10:11], v[150:151]
	v_pk_mul_f32 v[6:7], v[6:7], v[154:155]
	s_waitcnt lgkmcnt(0)
	v_pk_mul_f32 v[2:3], v[2:3], v[158:159]
	v_pk_mul_f32 v[0:1], v[0:1], v[156:157]
	v_pk_mul_f32 v[60:61], v[60:61], v[144:145]
	v_pk_mul_f32 v[56:57], v[56:57], v[148:149]
	v_pk_mul_f32 v[52:53], v[52:53], v[152:153]
	v_pk_mul_f32 v[62:63], v[62:63], v[146:147]
	v_pk_mul_f32 v[58:59], v[58:59], v[150:151]
	v_pk_mul_f32 v[54:55], v[54:55], v[154:155]
	v_pk_mul_f32 v[50:51], v[50:51], v[158:159]
	v_pk_mul_f32 v[48:49], v[48:49], v[156:157]
	v_pk_mul_f32 v[44:45], v[44:45], v[144:145]
	v_pk_mul_f32 v[40:41], v[40:41], v[148:149]
	v_pk_mul_f32 v[36:37], v[36:37], v[152:153]
	v_pk_mul_f32 v[46:47], v[46:47], v[146:147]
	v_pk_mul_f32 v[42:43], v[42:43], v[150:151]
	v_pk_mul_f32 v[38:39], v[38:39], v[154:155]
	v_pk_mul_f32 v[34:35], v[34:35], v[158:159]
	v_pk_mul_f32 v[32:33], v[32:33], v[156:157]
	v_pk_mul_f32 v[28:29], v[28:29], v[144:145]
	v_pk_mul_f32 v[24:25], v[24:25], v[148:149]
	v_pk_mul_f32 v[20:21], v[20:21], v[152:153]
	v_pk_mul_f32 v[30:31], v[30:31], v[146:147]
	v_pk_mul_f32 v[26:27], v[26:27], v[150:151]
	v_pk_mul_f32 v[22:23], v[22:23], v[154:155]
	v_pk_mul_f32 v[18:19], v[18:19], v[158:159]
	v_pk_mul_f32 v[16:17], v[16:17], v[156:157]
